# code placement: the three GEMM K-loop heads aligned to 64 bytes (timing-only)
# baseline (speedup 1.0000x reference)
.LBB0_389:
	s_ashr_i32 s29, s28, 31
	s_lshl_b64 s[4:5], s[28:29], 19
	s_add_u32 s30, s12, s4
	s_addc_u32 s31, s13, s5
	s_and_b64 s[4:5], s[40:41], exec
	s_cselect_b32 s29, s31, s43
	s_cselect_b32 vcc_lo, s30, s42
	s_ashr_i32 s37, s36, 31
	s_lshl_b64 s[4:5], s[36:37], 19
	s_add_u32 s34, s17, s4
	s_addc_u32 s35, s70, s5
	s_and_b64 s[4:5], s[40:41], exec
	s_cselect_b32 s37, s35, s39
	s_cselect_b32 vcc_hi, s34, s38
	s_add_u32 s59, s38, 0x100
	v_mov_b32_e32 v74, 0
	s_addc_u32 s72, s39, 0
	s_mov_b32 s73, -2
	s_add_u32 s38, s42, 0x100
	s_addc_u32 s39, s43, 0
	s_add_i32 s4, 0, 0x10000
	s_cmp_eq_u32 s73, 12
	s_cselect_b32 s69, s29, s39
	s_cselect_b32 s68, vcc_lo, s38
	s_cselect_b32 s67, s37, s72
	s_cselect_b32 s66, vcc_hi, s59
	s_add_i32 s6, 0, 0x14000
	v_add_u32_e32 v142, s4, v251
	v_add_u32_e32 v158, s6, v251
	ds_read_b128 v[130:133], v142
	ds_read_b128 v[134:137], v142 offset:1024
	ds_read_b128 v[138:141], v142 offset:2048
	ds_read_b128 v[142:145], v142 offset:3072
	ds_read_b128 v[146:149], v158
	ds_read_b128 v[150:153], v158 offset:1024
	ds_read_b128 v[154:157], v158 offset:2048
	ds_read_b128 v[158:161], v158 offset:3072
	v_lshl_add_u64 v[194:195], s[42:43], 0, v[228:229]
	s_add_i32 m0, s75, 0xc000
	ds_read_b128 v[162:165], v244
	ds_read_b128 v[166:169], v244 offset:1024
	ds_read_b128 v[170:173], v244 offset:2048
	ds_read_b128 v[174:177], v244 offset:3072
	ds_read_b128 v[178:181], v244 offset:4096
	ds_read_b128 v[182:185], v244 offset:5120
	ds_read_b128 v[186:189], v244 offset:6144
	ds_read_b128 v[190:193], v244 offset:7168
	global_load_lds_dwordx4 v[194:195], off
	v_lshl_add_u64 v[194:195], s[42:43], 0, v[230:231]
	s_add_i32 m0, s75, 0xe000
	s_nop 0
	global_load_lds_dwordx4 v[194:195], off
	s_waitcnt vmcnt(8)
	s_waitcnt lgkmcnt(0)
	s_barrier
	s_setprio 1
	s_waitcnt lgkmcnt(0)
	v_mfma_f32_16x16x32_bf16 v[114:117], v[130:133], v[162:165], 0
	v_mfma_f32_16x16x32_bf16 v[122:125], v[138:141], v[162:165], 0
	v_mfma_f32_16x16x32_bf16 v[118:121], v[130:133], v[170:173], 0
	v_mfma_f32_16x16x32_bf16 v[126:129], v[138:141], v[170:173], 0
	v_mfma_f32_16x16x32_bf16 v[54:57], v[130:133], v[178:181], 0
	v_mfma_f32_16x16x32_bf16 v[70:73], v[138:141], v[178:181], 0
	v_mfma_f32_16x16x32_bf16 v[50:53], v[130:133], v[186:189], 0
	v_mfma_f32_16x16x32_bf16 v[66:69], v[138:141], v[186:189], 0
	v_mfma_f32_16x16x32_bf16 v[114:117], v[134:137], v[166:169], v[114:117]
	v_mfma_f32_16x16x32_bf16 v[122:125], v[142:145], v[166:169], v[122:125]
	v_mfma_f32_16x16x32_bf16 v[118:121], v[134:137], v[174:177], v[118:121]
	v_mfma_f32_16x16x32_bf16 v[126:129], v[142:145], v[174:177], v[126:129]
	v_mfma_f32_16x16x32_bf16 v[54:57], v[134:137], v[182:185], v[54:57]
	v_mfma_f32_16x16x32_bf16 v[70:73], v[142:145], v[182:185], v[70:73]
	v_mfma_f32_16x16x32_bf16 v[50:53], v[134:137], v[190:193], v[50:53]
	v_mfma_f32_16x16x32_bf16 v[66:69], v[142:145], v[190:193], v[66:69]
	s_setprio 0
	s_setprio 1
	v_mfma_f32_16x16x32_bf16 v[106:109], v[146:149], v[162:165], 0
	v_mfma_f32_16x16x32_bf16 v[42:45], v[154:157], v[162:165], 0
	v_mfma_f32_16x16x32_bf16 v[110:113], v[146:149], v[170:173], 0
	v_mfma_f32_16x16x32_bf16 v[46:49], v[154:157], v[170:173], 0
	v_mfma_f32_16x16x32_bf16 v[30:33], v[146:149], v[178:181], 0
	v_mfma_f32_16x16x32_bf16 v[14:17], v[154:157], v[178:181], 0
	v_mfma_f32_16x16x32_bf16 v[26:29], v[146:149], v[186:189], 0
	v_mfma_f32_16x16x32_bf16 v[10:13], v[154:157], v[186:189], 0
	v_mfma_f32_16x16x32_bf16 v[106:109], v[150:153], v[166:169], v[106:109]
	v_mfma_f32_16x16x32_bf16 v[42:45], v[158:161], v[166:169], v[42:45]
	v_mfma_f32_16x16x32_bf16 v[110:113], v[150:153], v[174:177], v[110:113]
	v_mfma_f32_16x16x32_bf16 v[46:49], v[158:161], v[174:177], v[46:49]
	v_mfma_f32_16x16x32_bf16 v[30:33], v[150:153], v[182:185], v[30:33]
	v_mfma_f32_16x16x32_bf16 v[14:17], v[158:161], v[182:185], v[14:17]
	v_mfma_f32_16x16x32_bf16 v[26:29], v[150:153], v[190:193], v[26:29]
	s_barrier
	v_mfma_f32_16x16x32_bf16 v[10:13], v[158:161], v[190:193], v[10:13]
	s_setprio 0
	s_add_i32 s4, s4, s74
	v_lshl_add_u64 v[194:195], s[66:67], 0, v[0:1]
	s_mov_b32 m0, s4
	ds_read_b128 v[162:165], v244 offset:16384
	ds_read_b128 v[166:169], v244 offset:17408
	ds_read_b128 v[170:173], v244 offset:18432
	ds_read_b128 v[174:177], v244 offset:19456
	ds_read_b128 v[178:181], v244 offset:20480
	ds_read_b128 v[182:185], v244 offset:21504
	ds_read_b128 v[186:189], v244 offset:22528
	ds_read_b128 v[190:193], v244 offset:23552
	global_load_lds_dwordx4 v[194:195], off
	s_add_i32 m0, s4, 0x2000
	s_add_u32 s4, s66, 0x40000
	v_lshl_add_u64 v[196:197], s[66:67], 0, v[224:225]
	s_addc_u32 s5, s67, 0
	s_add_i32 s6, s6, s74
	global_load_lds_dwordx4 v[196:197], off
	v_lshl_add_u64 v[198:199], s[4:5], 0, v[0:1]
	s_mov_b32 m0, s6
	v_lshl_add_u64 v[200:201], s[68:69], 0, v[222:223]
	global_load_lds_dwordx4 v[198:199], off
	v_lshl_add_u64 v[198:199], s[4:5], 0, v[224:225]
	s_add_i32 m0, s6, 0x2000
	s_nop 0
	global_load_lds_dwordx4 v[198:199], off
	v_lshl_add_u64 v[198:199], s[68:69], 0, v[226:227]
	s_mov_b32 m0, s75
	s_nop 0
	global_load_lds_dwordx4 v[198:199], off
	s_mov_b32 m0, s76
	s_nop 0
	global_load_lds_dwordx4 v[200:201], off
	s_waitcnt vmcnt(8)
	s_waitcnt lgkmcnt(0)
	s_barrier
	s_setprio 1
	s_waitcnt lgkmcnt(0)
	v_mfma_f32_16x16x32_bf16 v[38:41], v[130:133], v[162:165], 0
	v_mfma_f32_16x16x32_bf16 v[62:65], v[138:141], v[162:165], 0
	v_mfma_f32_16x16x32_bf16 v[34:37], v[130:133], v[170:173], 0
	v_mfma_f32_16x16x32_bf16 v[58:61], v[138:141], v[170:173], 0
	v_mfma_f32_16x16x32_bf16 v[102:105], v[130:133], v[178:181], 0
	v_mfma_f32_16x16x32_bf16 v[98:101], v[138:141], v[178:181], 0
	v_mfma_f32_16x16x32_bf16 v[94:97], v[130:133], v[186:189], 0
	v_mfma_f32_16x16x32_bf16 v[90:93], v[138:141], v[186:189], 0
	v_mfma_f32_16x16x32_bf16 v[38:41], v[134:137], v[166:169], v[38:41]
	v_mfma_f32_16x16x32_bf16 v[62:65], v[142:145], v[166:169], v[62:65]
	v_mfma_f32_16x16x32_bf16 v[34:37], v[134:137], v[174:177], v[34:37]
	v_mfma_f32_16x16x32_bf16 v[58:61], v[142:145], v[174:177], v[58:61]
	v_mfma_f32_16x16x32_bf16 v[102:105], v[134:137], v[182:185], v[102:105]
	v_mfma_f32_16x16x32_bf16 v[98:101], v[142:145], v[182:185], v[98:101]
	v_mfma_f32_16x16x32_bf16 v[94:97], v[134:137], v[190:193], v[94:97]
	v_mfma_f32_16x16x32_bf16 v[90:93], v[142:145], v[190:193], v[90:93]
	s_setprio 0
	s_setprio 1
	v_mfma_f32_16x16x32_bf16 v[22:25], v[146:149], v[162:165], 0
	v_mfma_f32_16x16x32_bf16 v[6:9], v[154:157], v[162:165], 0
	v_mfma_f32_16x16x32_bf16 v[18:21], v[146:149], v[170:173], 0
	v_mfma_f32_16x16x32_bf16 v[2:5], v[154:157], v[170:173], 0
	v_mfma_f32_16x16x32_bf16 v[86:89], v[146:149], v[178:181], 0
	v_mfma_f32_16x16x32_bf16 v[82:85], v[154:157], v[178:181], 0
	v_mfma_f32_16x16x32_bf16 v[78:81], v[146:149], v[186:189], 0
	v_mfma_f32_16x16x32_bf16 v[74:77], v[154:157], v[186:189], 0
	v_mfma_f32_16x16x32_bf16 v[22:25], v[150:153], v[166:169], v[22:25]
	v_mfma_f32_16x16x32_bf16 v[6:9], v[158:161], v[166:169], v[6:9]
	v_mfma_f32_16x16x32_bf16 v[18:21], v[150:153], v[174:177], v[18:21]
	v_mfma_f32_16x16x32_bf16 v[2:5], v[158:161], v[174:177], v[2:5]
	v_mfma_f32_16x16x32_bf16 v[86:89], v[150:153], v[182:185], v[86:89]
	v_mfma_f32_16x16x32_bf16 v[82:85], v[158:161], v[182:185], v[82:85]
	v_mfma_f32_16x16x32_bf16 v[78:81], v[150:153], v[190:193], v[78:81]
	s_barrier
	v_mfma_f32_16x16x32_bf16 v[74:77], v[158:161], v[190:193], v[74:77]
	s_setprio 0
	s_add_i32 s6, 0, 0x18000
	s_add_i32 s7, 0, 0x1c000
	v_add_u32_e32 v142, s6, v251
	v_add_u32_e32 v158, s7, v251
	ds_read_b128 v[130:133], v142
	ds_read_b128 v[134:137], v142 offset:1024
	ds_read_b128 v[138:141], v142 offset:2048
	ds_read_b128 v[142:145], v142 offset:3072
	ds_read_b128 v[146:149], v158
	ds_read_b128 v[150:153], v158 offset:1024
	ds_read_b128 v[154:157], v158 offset:2048
	ds_read_b128 v[158:161], v158 offset:3072
	s_add_u32 s4, s68, 0x2000
	s_addc_u32 s5, s69, 0
	s_mov_b32 m0, s77
	v_lshl_add_u64 v[202:203], s[4:5], 0, v[226:227]
	ds_read_b128 v[162:165], v244 offset:32768
	ds_read_b128 v[166:169], v244 offset:33792
	ds_read_b128 v[170:173], v244 offset:34816
	ds_read_b128 v[174:177], v244 offset:35840
	ds_read_b128 v[178:181], v244 offset:36864
	ds_read_b128 v[182:185], v244 offset:37888
	ds_read_b128 v[186:189], v244 offset:38912
	ds_read_b128 v[190:193], v244 offset:39936
	global_load_lds_dwordx4 v[202:203], off
	v_lshl_add_u64 v[202:203], s[4:5], 0, v[222:223]
	s_mov_b32 m0, s78
	s_nop 0
	global_load_lds_dwordx4 v[202:203], off
	s_waitcnt vmcnt(8)
	s_waitcnt lgkmcnt(0)
	s_barrier
	s_setprio 1
	s_waitcnt lgkmcnt(0)
	v_mfma_f32_16x16x32_bf16 v[114:117], v[130:133], v[162:165], v[114:117]
	v_mfma_f32_16x16x32_bf16 v[122:125], v[138:141], v[162:165], v[122:125]
	v_mfma_f32_16x16x32_bf16 v[118:121], v[130:133], v[170:173], v[118:121]
	v_mfma_f32_16x16x32_bf16 v[126:129], v[138:141], v[170:173], v[126:129]
	v_mfma_f32_16x16x32_bf16 v[54:57], v[130:133], v[178:181], v[54:57]
	v_mfma_f32_16x16x32_bf16 v[70:73], v[138:141], v[178:181], v[70:73]
	v_mfma_f32_16x16x32_bf16 v[50:53], v[130:133], v[186:189], v[50:53]
	v_mfma_f32_16x16x32_bf16 v[66:69], v[138:141], v[186:189], v[66:69]
	v_mfma_f32_16x16x32_bf16 v[114:117], v[134:137], v[166:169], v[114:117]
	v_mfma_f32_16x16x32_bf16 v[122:125], v[142:145], v[166:169], v[122:125]
	v_mfma_f32_16x16x32_bf16 v[118:121], v[134:137], v[174:177], v[118:121]
	v_mfma_f32_16x16x32_bf16 v[126:129], v[142:145], v[174:177], v[126:129]
	v_mfma_f32_16x16x32_bf16 v[54:57], v[134:137], v[182:185], v[54:57]
	v_mfma_f32_16x16x32_bf16 v[70:73], v[142:145], v[182:185], v[70:73]
	v_mfma_f32_16x16x32_bf16 v[50:53], v[134:137], v[190:193], v[50:53]
	v_mfma_f32_16x16x32_bf16 v[66:69], v[142:145], v[190:193], v[66:69]
	s_setprio 0
	s_setprio 1
	v_mfma_f32_16x16x32_bf16 v[106:109], v[146:149], v[162:165], v[106:109]
	v_mfma_f32_16x16x32_bf16 v[42:45], v[154:157], v[162:165], v[42:45]
	v_mfma_f32_16x16x32_bf16 v[110:113], v[146:149], v[170:173], v[110:113]
	v_mfma_f32_16x16x32_bf16 v[46:49], v[154:157], v[170:173], v[46:49]
	v_mfma_f32_16x16x32_bf16 v[30:33], v[146:149], v[178:181], v[30:33]
	v_mfma_f32_16x16x32_bf16 v[14:17], v[154:157], v[178:181], v[14:17]
	v_mfma_f32_16x16x32_bf16 v[26:29], v[146:149], v[186:189], v[26:29]
	v_mfma_f32_16x16x32_bf16 v[10:13], v[154:157], v[186:189], v[10:13]
	v_mfma_f32_16x16x32_bf16 v[106:109], v[150:153], v[166:169], v[106:109]
	v_mfma_f32_16x16x32_bf16 v[42:45], v[158:161], v[166:169], v[42:45]
	v_mfma_f32_16x16x32_bf16 v[110:113], v[150:153], v[174:177], v[110:113]
	v_mfma_f32_16x16x32_bf16 v[46:49], v[158:161], v[174:177], v[46:49]
	v_mfma_f32_16x16x32_bf16 v[30:33], v[150:153], v[182:185], v[30:33]
	v_mfma_f32_16x16x32_bf16 v[14:17], v[158:161], v[182:185], v[14:17]
	v_mfma_f32_16x16x32_bf16 v[26:29], v[150:153], v[190:193], v[26:29]
	s_barrier
	v_mfma_f32_16x16x32_bf16 v[10:13], v[158:161], v[190:193], v[10:13]
	s_setprio 0
	s_add_i32 s4, s6, s74
	v_lshl_add_u64 v[194:195], v[194:195], 0, s[82:83]
	s_mov_b32 m0, s4
	ds_read_b128 v[162:165], v244 offset:49152
	ds_read_b128 v[166:169], v244 offset:50176
	ds_read_b128 v[170:173], v244 offset:51200
	ds_read_b128 v[174:177], v244 offset:52224
	ds_read_b128 v[178:181], v244 offset:53248
	ds_read_b128 v[182:185], v244 offset:54272
	ds_read_b128 v[186:189], v244 offset:55296
	ds_read_b128 v[190:193], v244 offset:56320
	global_load_lds_dwordx4 v[194:195], off
	s_add_i32 m0, s4, 0x2000
	s_add_u32 s4, s66, 0x40080
	v_lshl_add_u64 v[194:195], v[196:197], 0, s[82:83]
	s_addc_u32 s5, s67, 0
	s_add_i32 s6, s7, s74
	global_load_lds_dwordx4 v[194:195], off
	v_lshl_add_u64 v[194:195], s[4:5], 0, v[0:1]
	s_mov_b32 m0, s6
	s_nop 0
	global_load_lds_dwordx4 v[194:195], off
	v_lshl_add_u64 v[194:195], s[4:5], 0, v[224:225]
	s_add_i32 m0, s6, 0x2000
	s_nop 0
	global_load_lds_dwordx4 v[194:195], off
	v_lshl_add_u64 v[194:195], v[198:199], 0, s[82:83]
	s_mov_b32 m0, s94
	s_nop 0
	global_load_lds_dwordx4 v[194:195], off
	v_lshl_add_u64 v[194:195], v[200:201], 0, s[82:83]
	s_mov_b32 m0, s95
	s_nop 0
	global_load_lds_dwordx4 v[194:195], off
	s_waitcnt vmcnt(8)
	s_waitcnt lgkmcnt(0)
	s_barrier
	s_setprio 1
	s_waitcnt lgkmcnt(0)
	v_mfma_f32_16x16x32_bf16 v[38:41], v[130:133], v[162:165], v[38:41]
	v_mfma_f32_16x16x32_bf16 v[62:65], v[138:141], v[162:165], v[62:65]
	v_mfma_f32_16x16x32_bf16 v[34:37], v[130:133], v[170:173], v[34:37]
	v_mfma_f32_16x16x32_bf16 v[58:61], v[138:141], v[170:173], v[58:61]
	v_mfma_f32_16x16x32_bf16 v[102:105], v[130:133], v[178:181], v[102:105]
	v_mfma_f32_16x16x32_bf16 v[98:101], v[138:141], v[178:181], v[98:101]
	v_mfma_f32_16x16x32_bf16 v[94:97], v[130:133], v[186:189], v[94:97]
	v_mfma_f32_16x16x32_bf16 v[90:93], v[138:141], v[186:189], v[90:93]
	v_mfma_f32_16x16x32_bf16 v[38:41], v[134:137], v[166:169], v[38:41]
	v_mfma_f32_16x16x32_bf16 v[62:65], v[142:145], v[166:169], v[62:65]
	v_mfma_f32_16x16x32_bf16 v[34:37], v[134:137], v[174:177], v[34:37]
	v_mfma_f32_16x16x32_bf16 v[58:61], v[142:145], v[174:177], v[58:61]
	v_mfma_f32_16x16x32_bf16 v[102:105], v[134:137], v[182:185], v[102:105]
	v_mfma_f32_16x16x32_bf16 v[98:101], v[142:145], v[182:185], v[98:101]
	v_mfma_f32_16x16x32_bf16 v[94:97], v[134:137], v[190:193], v[94:97]
	v_mfma_f32_16x16x32_bf16 v[90:93], v[142:145], v[190:193], v[90:93]
	s_setprio 0
	s_setprio 1
	v_mfma_f32_16x16x32_bf16 v[22:25], v[146:149], v[162:165], v[22:25]
	v_mfma_f32_16x16x32_bf16 v[6:9], v[154:157], v[162:165], v[6:9]
	v_mfma_f32_16x16x32_bf16 v[18:21], v[146:149], v[170:173], v[18:21]
	v_mfma_f32_16x16x32_bf16 v[2:5], v[154:157], v[170:173], v[2:5]
	v_mfma_f32_16x16x32_bf16 v[86:89], v[146:149], v[178:181], v[86:89]
	v_mfma_f32_16x16x32_bf16 v[82:85], v[154:157], v[178:181], v[82:85]
	v_mfma_f32_16x16x32_bf16 v[78:81], v[146:149], v[186:189], v[78:81]
	v_mfma_f32_16x16x32_bf16 v[74:77], v[154:157], v[186:189], v[74:77]
	v_mfma_f32_16x16x32_bf16 v[22:25], v[150:153], v[166:169], v[22:25]
	v_mfma_f32_16x16x32_bf16 v[6:9], v[158:161], v[166:169], v[6:9]
	v_mfma_f32_16x16x32_bf16 v[18:21], v[150:153], v[174:177], v[18:21]
	v_mfma_f32_16x16x32_bf16 v[2:5], v[158:161], v[174:177], v[2:5]
	v_mfma_f32_16x16x32_bf16 v[86:89], v[150:153], v[182:185], v[86:89]
	v_mfma_f32_16x16x32_bf16 v[82:85], v[158:161], v[182:185], v[82:85]
	v_mfma_f32_16x16x32_bf16 v[78:81], v[150:153], v[190:193], v[78:81]
	s_barrier
	v_mfma_f32_16x16x32_bf16 v[74:77], v[158:161], v[190:193], v[74:77]
	s_setprio 0
	s_add_i32 s73, s73, 2
	s_add_u32 s59, s59, 0x100
	s_addc_u32 s72, s72, 0
	s_cmp_gt_u32 s73, 13
	s_mov_b64 s[42:43], s[38:39]
	.p2align 6

.LBB0_451:
	s_add_u32 s30, s30, 0x80
	s_addc_u32 s31, s31, 0
	s_add_u32 s42, s34, 0x100
	v_mov_b32_e32 v2, 0
	s_addc_u32 s43, s35, 0
	s_mov_b32 s34, 0
	s_waitcnt lgkmcnt(0)
	s_add_i32 s59, s34, 2
	s_add_u32 s4, s30, 0x80
	s_addc_u32 s5, s31, 0
	s_add_i32 s6, 0, 0x10000
	s_cmp_eq_u32 s53, s34
	s_cselect_b32 s35, s27, s5
	s_cselect_b32 s34, s26, s4
	s_cselect_b32 s5, s29, s43
	s_cselect_b32 s4, s28, s42
	s_add_i32 s7, 0, 0x14000
	v_add_u32_e32 v142, s6, v184
	v_add_u32_e32 v168, s7, v184
	ds_read_b128 v[130:133], v142
	ds_read_b128 v[134:137], v142 offset:1024
	ds_read_b128 v[138:141], v142 offset:2048
	ds_read_b128 v[142:145], v142 offset:3072
	ds_read_b128 v[146:149], v168
	ds_read_b128 v[150:153], v168 offset:1024
	ds_read_b128 v[154:157], v168 offset:2048
	ds_read_b128 v[168:171], v168 offset:3072
	v_lshl_add_u64 v[180:181], s[30:31], 0, v[164:165]
	s_add_i32 m0, s38, 0xc000
	ds_read_b128 v[172:175], v187
	ds_read_b128 v[176:179], v187 offset:1024
	ds_read_b128 v[188:191], v187 offset:2048
	ds_read_b128 v[192:195], v187 offset:3072
	ds_read_b128 v[196:199], v187 offset:4096
	ds_read_b128 v[200:203], v187 offset:5120
	ds_read_b128 v[204:207], v187 offset:6144
	ds_read_b128 v[222:225], v187 offset:7168
	global_load_lds_dwordx4 v[180:181], off
	v_lshl_add_u64 v[180:181], s[30:31], 0, v[166:167]
	s_add_i32 m0, s38, 0xe000
	s_nop 0
	global_load_lds_dwordx4 v[180:181], off
	s_waitcnt vmcnt(8)
	s_waitcnt lgkmcnt(0)
	s_barrier
	s_setprio 1
	s_waitcnt lgkmcnt(0)
	v_mfma_f32_16x16x32_bf16 v[126:129], v[130:133], v[172:175], 0
	v_mfma_f32_16x16x32_bf16 v[122:125], v[138:141], v[172:175], 0
	v_mfma_f32_16x16x32_bf16 v[110:113], v[130:133], v[188:191], 0
	v_mfma_f32_16x16x32_bf16 v[106:109], v[138:141], v[188:191], 0
	v_mfma_f32_16x16x32_bf16 v[98:101], v[130:133], v[196:199], 0
	v_mfma_f32_16x16x32_bf16 v[90:93], v[138:141], v[196:199], 0
	v_mfma_f32_16x16x32_bf16 v[82:85], v[130:133], v[204:207], 0
	v_mfma_f32_16x16x32_bf16 v[74:77], v[138:141], v[204:207], 0
	v_mfma_f32_16x16x32_bf16 v[126:129], v[134:137], v[176:179], v[126:129]
	v_mfma_f32_16x16x32_bf16 v[122:125], v[142:145], v[176:179], v[122:125]
	v_mfma_f32_16x16x32_bf16 v[110:113], v[134:137], v[192:195], v[110:113]
	v_mfma_f32_16x16x32_bf16 v[106:109], v[142:145], v[192:195], v[106:109]
	v_mfma_f32_16x16x32_bf16 v[98:101], v[134:137], v[200:203], v[98:101]
	v_mfma_f32_16x16x32_bf16 v[90:93], v[142:145], v[200:203], v[90:93]
	v_mfma_f32_16x16x32_bf16 v[82:85], v[134:137], v[222:225], v[82:85]
	v_mfma_f32_16x16x32_bf16 v[74:77], v[142:145], v[222:225], v[74:77]
	s_setprio 0
	s_setprio 1
	v_mfma_f32_16x16x32_bf16 v[118:121], v[146:149], v[172:175], 0
	v_mfma_f32_16x16x32_bf16 v[114:117], v[154:157], v[172:175], 0
	v_mfma_f32_16x16x32_bf16 v[102:105], v[146:149], v[188:191], 0
	v_mfma_f32_16x16x32_bf16 v[94:97], v[154:157], v[188:191], 0
	v_mfma_f32_16x16x32_bf16 v[86:89], v[146:149], v[196:199], 0
	v_mfma_f32_16x16x32_bf16 v[78:81], v[154:157], v[196:199], 0
	v_mfma_f32_16x16x32_bf16 v[70:73], v[146:149], v[204:207], 0
	v_mfma_f32_16x16x32_bf16 v[66:69], v[154:157], v[204:207], 0
	v_mfma_f32_16x16x32_bf16 v[118:121], v[150:153], v[176:179], v[118:121]
	v_mfma_f32_16x16x32_bf16 v[114:117], v[168:171], v[176:179], v[114:117]
	v_mfma_f32_16x16x32_bf16 v[102:105], v[150:153], v[192:195], v[102:105]
	v_mfma_f32_16x16x32_bf16 v[94:97], v[168:171], v[192:195], v[94:97]
	v_mfma_f32_16x16x32_bf16 v[86:89], v[150:153], v[200:203], v[86:89]
	v_mfma_f32_16x16x32_bf16 v[78:81], v[168:171], v[200:203], v[78:81]
	v_mfma_f32_16x16x32_bf16 v[70:73], v[150:153], v[222:225], v[70:73]
	s_barrier
	v_mfma_f32_16x16x32_bf16 v[66:69], v[168:171], v[222:225], v[66:69]
	s_setprio 0
	s_add_i32 s6, s6, s37
	v_lshl_add_u64 v[180:181], s[4:5], 0, v[0:1]
	s_mov_b32 m0, s6
	ds_read_b128 v[172:175], v187 offset:16384
	ds_read_b128 v[176:179], v187 offset:17408
	ds_read_b128 v[188:191], v187 offset:18432
	ds_read_b128 v[192:195], v187 offset:19456
	ds_read_b128 v[196:199], v187 offset:20480
	ds_read_b128 v[200:203], v187 offset:21504
	ds_read_b128 v[204:207], v187 offset:22528
	ds_read_b128 v[222:225], v187 offset:23552
	global_load_lds_dwordx4 v[180:181], off
	s_add_i32 m0, s6, 0x2000
	v_lshl_add_u64 v[208:209], s[4:5], 0, v[160:161]
	s_add_u32 s4, s4, s84
	s_addc_u32 s5, s5, 0
	s_add_i32 s6, s7, s37
	global_load_lds_dwordx4 v[208:209], off
	v_lshl_add_u64 v[226:227], s[4:5], 0, v[0:1]
	s_mov_b32 m0, s6
	v_lshl_add_u64 v[228:229], s[4:5], 0, v[160:161]
	global_load_lds_dwordx4 v[226:227], off
	s_add_i32 m0, s6, 0x2000
	v_lshl_add_u64 v[230:231], s[34:35], 0, v[162:163]
	global_load_lds_dwordx4 v[228:229], off
	s_mov_b32 m0, s38
	v_lshl_add_u64 v[232:233], s[34:35], 0, v[158:159]
	global_load_lds_dwordx4 v[230:231], off
	s_mov_b32 m0, s39
	s_nop 0
	global_load_lds_dwordx4 v[232:233], off
	s_waitcnt vmcnt(8)
	s_waitcnt lgkmcnt(0)
	s_barrier
	s_setprio 1
	s_waitcnt lgkmcnt(0)
	v_mfma_f32_16x16x32_bf16 v[62:65], v[130:133], v[172:175], 0
	v_mfma_f32_16x16x32_bf16 v[58:61], v[138:141], v[172:175], 0
	v_mfma_f32_16x16x32_bf16 v[46:49], v[130:133], v[188:191], 0
	v_mfma_f32_16x16x32_bf16 v[42:45], v[138:141], v[188:191], 0
	v_mfma_f32_16x16x32_bf16 v[34:37], v[130:133], v[196:199], 0
	v_mfma_f32_16x16x32_bf16 v[26:29], v[138:141], v[196:199], 0
	v_mfma_f32_16x16x32_bf16 v[18:21], v[130:133], v[204:207], 0
	v_mfma_f32_16x16x32_bf16 v[10:13], v[138:141], v[204:207], 0
	v_mfma_f32_16x16x32_bf16 v[62:65], v[134:137], v[176:179], v[62:65]
	v_mfma_f32_16x16x32_bf16 v[58:61], v[142:145], v[176:179], v[58:61]
	v_mfma_f32_16x16x32_bf16 v[46:49], v[134:137], v[192:195], v[46:49]
	v_mfma_f32_16x16x32_bf16 v[42:45], v[142:145], v[192:195], v[42:45]
	v_mfma_f32_16x16x32_bf16 v[34:37], v[134:137], v[200:203], v[34:37]
	v_mfma_f32_16x16x32_bf16 v[26:29], v[142:145], v[200:203], v[26:29]
	v_mfma_f32_16x16x32_bf16 v[18:21], v[134:137], v[222:225], v[18:21]
	v_mfma_f32_16x16x32_bf16 v[10:13], v[142:145], v[222:225], v[10:13]
	s_setprio 0
	s_setprio 1
	v_mfma_f32_16x16x32_bf16 v[54:57], v[146:149], v[172:175], 0
	v_mfma_f32_16x16x32_bf16 v[50:53], v[154:157], v[172:175], 0
	v_mfma_f32_16x16x32_bf16 v[38:41], v[146:149], v[188:191], 0
	v_mfma_f32_16x16x32_bf16 v[30:33], v[154:157], v[188:191], 0
	v_mfma_f32_16x16x32_bf16 v[22:25], v[146:149], v[196:199], 0
	v_mfma_f32_16x16x32_bf16 v[14:17], v[154:157], v[196:199], 0
	v_mfma_f32_16x16x32_bf16 v[6:9], v[146:149], v[204:207], 0
	v_mfma_f32_16x16x32_bf16 v[2:5], v[154:157], v[204:207], 0
	v_mfma_f32_16x16x32_bf16 v[54:57], v[150:153], v[176:179], v[54:57]
	v_mfma_f32_16x16x32_bf16 v[50:53], v[168:171], v[176:179], v[50:53]
	v_mfma_f32_16x16x32_bf16 v[38:41], v[150:153], v[192:195], v[38:41]
	v_mfma_f32_16x16x32_bf16 v[30:33], v[168:171], v[192:195], v[30:33]
	v_mfma_f32_16x16x32_bf16 v[22:25], v[150:153], v[200:203], v[22:25]
	v_mfma_f32_16x16x32_bf16 v[14:17], v[168:171], v[200:203], v[14:17]
	v_mfma_f32_16x16x32_bf16 v[6:9], v[150:153], v[222:225], v[6:9]
	s_barrier
	v_mfma_f32_16x16x32_bf16 v[2:5], v[168:171], v[222:225], v[2:5]
	s_setprio 0
	s_add_i32 s6, 0, 0x18000
	s_add_i32 s7, 0, 0x1c000
	v_add_u32_e32 v142, s6, v184
	v_add_u32_e32 v168, s7, v184
	ds_read_b128 v[130:133], v142
	ds_read_b128 v[134:137], v142 offset:1024
	ds_read_b128 v[138:141], v142 offset:2048
	ds_read_b128 v[142:145], v142 offset:3072
	ds_read_b128 v[146:149], v168
	ds_read_b128 v[150:153], v168 offset:1024
	ds_read_b128 v[154:157], v168 offset:2048
	ds_read_b128 v[168:171], v168 offset:3072
	s_add_u32 s4, s34, s84
	s_addc_u32 s5, s35, 0
	s_mov_b32 m0, s45
	v_lshl_add_u64 v[234:235], s[4:5], 0, v[162:163]
	ds_read_b128 v[172:175], v187 offset:32768
	ds_read_b128 v[176:179], v187 offset:33792
	ds_read_b128 v[188:191], v187 offset:34816
	ds_read_b128 v[192:195], v187 offset:35840
	ds_read_b128 v[196:199], v187 offset:36864
	ds_read_b128 v[200:203], v187 offset:37888
	ds_read_b128 v[204:207], v187 offset:38912
	ds_read_b128 v[222:225], v187 offset:39936
	global_load_lds_dwordx4 v[234:235], off
	v_lshl_add_u64 v[234:235], s[4:5], 0, v[158:159]
	s_mov_b32 m0, s46
	s_nop 0
	global_load_lds_dwordx4 v[234:235], off
	s_waitcnt vmcnt(8)
	s_waitcnt lgkmcnt(0)
	s_barrier
	s_setprio 1
	s_waitcnt lgkmcnt(0)
	v_mfma_f32_16x16x32_bf16 v[126:129], v[130:133], v[172:175], v[126:129]
	v_mfma_f32_16x16x32_bf16 v[122:125], v[138:141], v[172:175], v[122:125]
	v_mfma_f32_16x16x32_bf16 v[110:113], v[130:133], v[188:191], v[110:113]
	v_mfma_f32_16x16x32_bf16 v[106:109], v[138:141], v[188:191], v[106:109]
	v_mfma_f32_16x16x32_bf16 v[98:101], v[130:133], v[196:199], v[98:101]
	v_mfma_f32_16x16x32_bf16 v[90:93], v[138:141], v[196:199], v[90:93]
	v_mfma_f32_16x16x32_bf16 v[82:85], v[130:133], v[204:207], v[82:85]
	v_mfma_f32_16x16x32_bf16 v[74:77], v[138:141], v[204:207], v[74:77]
	v_mfma_f32_16x16x32_bf16 v[126:129], v[134:137], v[176:179], v[126:129]
	v_mfma_f32_16x16x32_bf16 v[122:125], v[142:145], v[176:179], v[122:125]
	v_mfma_f32_16x16x32_bf16 v[110:113], v[134:137], v[192:195], v[110:113]
	v_mfma_f32_16x16x32_bf16 v[106:109], v[142:145], v[192:195], v[106:109]
	v_mfma_f32_16x16x32_bf16 v[98:101], v[134:137], v[200:203], v[98:101]
	v_mfma_f32_16x16x32_bf16 v[90:93], v[142:145], v[200:203], v[90:93]
	v_mfma_f32_16x16x32_bf16 v[82:85], v[134:137], v[222:225], v[82:85]
	v_mfma_f32_16x16x32_bf16 v[74:77], v[142:145], v[222:225], v[74:77]
	s_setprio 0
	s_setprio 1
	v_mfma_f32_16x16x32_bf16 v[118:121], v[146:149], v[172:175], v[118:121]
	v_mfma_f32_16x16x32_bf16 v[114:117], v[154:157], v[172:175], v[114:117]
	v_mfma_f32_16x16x32_bf16 v[102:105], v[146:149], v[188:191], v[102:105]
	v_mfma_f32_16x16x32_bf16 v[94:97], v[154:157], v[188:191], v[94:97]
	v_mfma_f32_16x16x32_bf16 v[86:89], v[146:149], v[196:199], v[86:89]
	v_mfma_f32_16x16x32_bf16 v[78:81], v[154:157], v[196:199], v[78:81]
	v_mfma_f32_16x16x32_bf16 v[70:73], v[146:149], v[204:207], v[70:73]
	v_mfma_f32_16x16x32_bf16 v[66:69], v[154:157], v[204:207], v[66:69]
	v_mfma_f32_16x16x32_bf16 v[118:121], v[150:153], v[176:179], v[118:121]
	v_mfma_f32_16x16x32_bf16 v[114:117], v[168:171], v[176:179], v[114:117]
	v_mfma_f32_16x16x32_bf16 v[102:105], v[150:153], v[192:195], v[102:105]
	v_mfma_f32_16x16x32_bf16 v[94:97], v[168:171], v[192:195], v[94:97]
	v_mfma_f32_16x16x32_bf16 v[86:89], v[150:153], v[200:203], v[86:89]
	v_mfma_f32_16x16x32_bf16 v[78:81], v[168:171], v[200:203], v[78:81]
	v_mfma_f32_16x16x32_bf16 v[70:73], v[150:153], v[222:225], v[70:73]
	s_barrier
	v_mfma_f32_16x16x32_bf16 v[66:69], v[168:171], v[222:225], v[66:69]
	s_setprio 0
	s_add_i32 s4, s6, s37
	v_lshl_add_u64 v[180:181], v[180:181], 0, s[82:83]
	s_mov_b32 m0, s4
	ds_read_b128 v[172:175], v187 offset:49152
	ds_read_b128 v[176:179], v187 offset:50176
	ds_read_b128 v[188:191], v187 offset:51200
	ds_read_b128 v[192:195], v187 offset:52224
	ds_read_b128 v[196:199], v187 offset:53248
	ds_read_b128 v[200:203], v187 offset:54272
	ds_read_b128 v[204:207], v187 offset:55296
	ds_read_b128 v[222:225], v187 offset:56320
	global_load_lds_dwordx4 v[180:181], off
	v_lshl_add_u64 v[180:181], v[208:209], 0, s[82:83]
	s_add_i32 m0, s4, 0x2000
	s_add_i32 s4, s7, s37
	global_load_lds_dwordx4 v[180:181], off
	v_lshl_add_u64 v[180:181], v[226:227], 0, s[82:83]
	s_mov_b32 m0, s4
	s_nop 0
	global_load_lds_dwordx4 v[180:181], off
	v_lshl_add_u64 v[180:181], v[228:229], 0, s[82:83]
	s_add_i32 m0, s4, 0x2000
	s_nop 0
	global_load_lds_dwordx4 v[180:181], off
	v_lshl_add_u64 v[180:181], v[230:231], 0, s[82:83]
	s_mov_b32 m0, s51
	s_nop 0
	global_load_lds_dwordx4 v[180:181], off
	v_lshl_add_u64 v[180:181], v[232:233], 0, s[82:83]
	s_mov_b32 m0, s52
	s_nop 0
	global_load_lds_dwordx4 v[180:181], off
	s_waitcnt vmcnt(8)
	s_waitcnt lgkmcnt(0)
	s_barrier
	s_setprio 1
	s_waitcnt lgkmcnt(0)
	v_mfma_f32_16x16x32_bf16 v[62:65], v[130:133], v[172:175], v[62:65]
	v_mfma_f32_16x16x32_bf16 v[58:61], v[138:141], v[172:175], v[58:61]
	v_mfma_f32_16x16x32_bf16 v[46:49], v[130:133], v[188:191], v[46:49]
	v_mfma_f32_16x16x32_bf16 v[42:45], v[138:141], v[188:191], v[42:45]
	v_mfma_f32_16x16x32_bf16 v[34:37], v[130:133], v[196:199], v[34:37]
	v_mfma_f32_16x16x32_bf16 v[26:29], v[138:141], v[196:199], v[26:29]
	v_mfma_f32_16x16x32_bf16 v[18:21], v[130:133], v[204:207], v[18:21]
	v_mfma_f32_16x16x32_bf16 v[10:13], v[138:141], v[204:207], v[10:13]
	v_mfma_f32_16x16x32_bf16 v[62:65], v[134:137], v[176:179], v[62:65]
	v_mfma_f32_16x16x32_bf16 v[58:61], v[142:145], v[176:179], v[58:61]
	v_mfma_f32_16x16x32_bf16 v[46:49], v[134:137], v[192:195], v[46:49]
	v_mfma_f32_16x16x32_bf16 v[42:45], v[142:145], v[192:195], v[42:45]
	v_mfma_f32_16x16x32_bf16 v[34:37], v[134:137], v[200:203], v[34:37]
	v_mfma_f32_16x16x32_bf16 v[26:29], v[142:145], v[200:203], v[26:29]
	v_mfma_f32_16x16x32_bf16 v[18:21], v[134:137], v[222:225], v[18:21]
	v_mfma_f32_16x16x32_bf16 v[10:13], v[142:145], v[222:225], v[10:13]
	s_setprio 0
	s_setprio 1
	v_mfma_f32_16x16x32_bf16 v[54:57], v[146:149], v[172:175], v[54:57]
	v_mfma_f32_16x16x32_bf16 v[50:53], v[154:157], v[172:175], v[50:53]
	v_mfma_f32_16x16x32_bf16 v[38:41], v[146:149], v[188:191], v[38:41]
	v_mfma_f32_16x16x32_bf16 v[30:33], v[154:157], v[188:191], v[30:33]
	v_mfma_f32_16x16x32_bf16 v[22:25], v[146:149], v[196:199], v[22:25]
	v_mfma_f32_16x16x32_bf16 v[14:17], v[154:157], v[196:199], v[14:17]
	v_mfma_f32_16x16x32_bf16 v[6:9], v[146:149], v[204:207], v[6:9]
	v_mfma_f32_16x16x32_bf16 v[2:5], v[154:157], v[204:207], v[2:5]
	v_mfma_f32_16x16x32_bf16 v[54:57], v[150:153], v[176:179], v[54:57]
	v_mfma_f32_16x16x32_bf16 v[50:53], v[168:171], v[176:179], v[50:53]
	v_mfma_f32_16x16x32_bf16 v[38:41], v[150:153], v[192:195], v[38:41]
	v_mfma_f32_16x16x32_bf16 v[30:33], v[168:171], v[192:195], v[30:33]
	v_mfma_f32_16x16x32_bf16 v[22:25], v[150:153], v[200:203], v[22:25]
	v_mfma_f32_16x16x32_bf16 v[14:17], v[168:171], v[200:203], v[14:17]
	v_mfma_f32_16x16x32_bf16 v[6:9], v[150:153], v[222:225], v[6:9]
	s_barrier
	v_mfma_f32_16x16x32_bf16 v[2:5], v[168:171], v[222:225], v[2:5]
	s_setprio 0
	s_add_u32 s30, s30, 0x100
	s_addc_u32 s31, s31, 0
	s_add_u32 s42, s42, 0x100
	s_addc_u32 s43, s43, 0
	s_cmp_ge_u32 s59, s48
	s_mov_b32 s34, s59
	.p2align 6

.LBB0_488:
	s_ashr_i32 s25, s24, 31
	s_lshl_b64 s[4:5], s[24:25], 19
	s_add_u32 s26, s12, s4
	s_addc_u32 s27, s13, s5
	s_and_b64 s[4:5], s[40:41], exec
	s_cselect_b32 s25, s27, s31
	s_cselect_b32 s66, s26, s30
	s_ashr_i32 s23, s22, 31
	s_lshl_b64 s[4:5], s[22:23], 19
	s_add_u32 s28, s39, s4
	s_addc_u32 s29, s42, s5
	s_and_b64 s[4:5], s[40:41], exec
	s_cselect_b32 s23, s29, s35
	s_cselect_b32 s67, s28, s34
	s_add_u32 s30, s30, 0x40080
	s_addc_u32 s31, s31, 0
	s_add_u32 s68, s34, 0x100
	v_mov_b32_e32 v2, 0
	s_addc_u32 s69, s35, 0
	s_mov_b32 s59, -2
	s_add_u32 s4, s30, 0xfffc0080
	s_addc_u32 s5, s31, -1
	s_add_i32 s6, 0, 0x10000
	s_cmp_eq_u32 s59, 12
	s_cselect_b32 s37, s25, s5
	s_cselect_b32 s36, s66, s4
	s_cselect_b32 s35, s23, s69
	s_cselect_b32 s34, s67, s68
	s_add_i32 s7, 0, 0x14000
	v_add_u32_e32 v156, s6, v146
	v_add_u32_e32 v172, s7, v146
	ds_read_b128 v[140:143], v156
	ds_read_b128 v[148:151], v156 offset:1024
	ds_read_b128 v[152:155], v156 offset:2048
	ds_read_b128 v[156:159], v156 offset:3072
	ds_read_b128 v[160:163], v172
	ds_read_b128 v[164:167], v172 offset:1024
	ds_read_b128 v[168:171], v172 offset:2048
	ds_read_b128 v[172:175], v172 offset:3072
	v_lshl_add_u64 v[208:209], s[30:31], 0, v[136:137]
	s_add_i32 m0, s43, 0xc000
	ds_read_b128 v[176:179], v147
	ds_read_b128 v[180:183], v147 offset:1024
	ds_read_b128 v[184:187], v147 offset:2048
	ds_read_b128 v[188:191], v147 offset:3072
	ds_read_b128 v[192:195], v147 offset:4096
	ds_read_b128 v[196:199], v147 offset:5120
	ds_read_b128 v[200:203], v147 offset:6144
	ds_read_b128 v[204:207], v147 offset:7168
	global_load_lds_dwordx4 v[208:209], off
	v_lshl_add_u64 v[208:209], s[30:31], 0, v[138:139]
	s_add_i32 m0, s43, 0xe000
	s_nop 0
	global_load_lds_dwordx4 v[208:209], off
	s_waitcnt vmcnt(24)
	s_waitcnt lgkmcnt(0)
	s_barrier
	s_setprio 1
	s_waitcnt lgkmcnt(0)
	v_mfma_f32_16x16x32_bf16 v[126:129], v[140:143], v[176:179], 0
	v_mfma_f32_16x16x32_bf16 v[122:125], v[152:155], v[176:179], 0
	v_mfma_f32_16x16x32_bf16 v[118:121], v[140:143], v[184:187], 0
	v_mfma_f32_16x16x32_bf16 v[110:113], v[152:155], v[184:187], 0
	v_mfma_f32_16x16x32_bf16 v[102:105], v[140:143], v[192:195], 0
	v_mfma_f32_16x16x32_bf16 v[94:97], v[152:155], v[192:195], 0
	v_mfma_f32_16x16x32_bf16 v[86:89], v[140:143], v[200:203], 0
	v_mfma_f32_16x16x32_bf16 v[78:81], v[152:155], v[200:203], 0
	v_mfma_f32_16x16x32_bf16 v[126:129], v[148:151], v[180:183], v[126:129]
	v_mfma_f32_16x16x32_bf16 v[122:125], v[156:159], v[180:183], v[122:125]
	v_mfma_f32_16x16x32_bf16 v[118:121], v[148:151], v[188:191], v[118:121]
	v_mfma_f32_16x16x32_bf16 v[110:113], v[156:159], v[188:191], v[110:113]
	v_mfma_f32_16x16x32_bf16 v[102:105], v[148:151], v[196:199], v[102:105]
	v_mfma_f32_16x16x32_bf16 v[94:97], v[156:159], v[196:199], v[94:97]
	v_mfma_f32_16x16x32_bf16 v[86:89], v[148:151], v[204:207], v[86:89]
	v_mfma_f32_16x16x32_bf16 v[78:81], v[156:159], v[204:207], v[78:81]
	s_setprio 0
	s_setprio 1
	v_mfma_f32_16x16x32_bf16 v[114:117], v[160:163], v[176:179], 0
	v_mfma_f32_16x16x32_bf16 v[106:109], v[168:171], v[176:179], 0
	v_mfma_f32_16x16x32_bf16 v[98:101], v[160:163], v[184:187], 0
	v_mfma_f32_16x16x32_bf16 v[90:93], v[168:171], v[184:187], 0
	v_mfma_f32_16x16x32_bf16 v[82:85], v[160:163], v[192:195], 0
	v_mfma_f32_16x16x32_bf16 v[74:77], v[168:171], v[192:195], 0
	v_mfma_f32_16x16x32_bf16 v[70:73], v[160:163], v[200:203], 0
	v_mfma_f32_16x16x32_bf16 v[66:69], v[168:171], v[200:203], 0
	v_mfma_f32_16x16x32_bf16 v[114:117], v[164:167], v[180:183], v[114:117]
	v_mfma_f32_16x16x32_bf16 v[106:109], v[172:175], v[180:183], v[106:109]
	v_mfma_f32_16x16x32_bf16 v[98:101], v[164:167], v[188:191], v[98:101]
	v_mfma_f32_16x16x32_bf16 v[90:93], v[172:175], v[188:191], v[90:93]
	v_mfma_f32_16x16x32_bf16 v[82:85], v[164:167], v[196:199], v[82:85]
	v_mfma_f32_16x16x32_bf16 v[74:77], v[172:175], v[196:199], v[74:77]
	v_mfma_f32_16x16x32_bf16 v[70:73], v[164:167], v[204:207], v[70:73]
	s_barrier
	v_mfma_f32_16x16x32_bf16 v[66:69], v[172:175], v[204:207], v[66:69]
	s_setprio 0
	s_add_i32 s4, s6, s38
	v_lshl_add_u64 v[208:209], s[34:35], 0, v[0:1]
	s_mov_b32 m0, s4
	ds_read_b128 v[176:179], v147 offset:16384
	ds_read_b128 v[180:183], v147 offset:17408
	ds_read_b128 v[184:187], v147 offset:18432
	ds_read_b128 v[188:191], v147 offset:19456
	ds_read_b128 v[192:195], v147 offset:20480
	ds_read_b128 v[196:199], v147 offset:21504
	ds_read_b128 v[200:203], v147 offset:22528
	ds_read_b128 v[204:207], v147 offset:23552
	global_load_lds_dwordx4 v[208:209], off
	s_add_i32 m0, s4, 0x2000
	s_add_u32 s4, s34, 0x40000
	v_lshl_add_u64 v[222:223], s[34:35], 0, v[132:133]
	s_addc_u32 s5, s35, 0
	s_add_i32 s6, s7, s38
	global_load_lds_dwordx4 v[222:223], off
	v_lshl_add_u64 v[224:225], s[4:5], 0, v[0:1]
	s_mov_b32 m0, s6
	v_lshl_add_u64 v[226:227], s[36:37], 0, v[130:131]
	global_load_lds_dwordx4 v[224:225], off
	v_lshl_add_u64 v[224:225], s[4:5], 0, v[132:133]
	s_add_i32 m0, s6, 0x2000
	s_nop 0
	global_load_lds_dwordx4 v[224:225], off
	v_lshl_add_u64 v[224:225], s[36:37], 0, v[134:135]
	s_mov_b32 m0, s43
	s_nop 0
	global_load_lds_dwordx4 v[224:225], off
	s_mov_b32 m0, s44
	s_nop 0
	global_load_lds_dwordx4 v[226:227], off
	s_waitcnt vmcnt(24)
	s_waitcnt lgkmcnt(0)
	s_barrier
	s_setprio 1
	s_waitcnt lgkmcnt(0)
	v_mfma_f32_16x16x32_bf16 v[62:65], v[140:143], v[176:179], 0
	v_mfma_f32_16x16x32_bf16 v[58:61], v[152:155], v[176:179], 0
	v_mfma_f32_16x16x32_bf16 v[54:57], v[140:143], v[184:187], 0
	v_mfma_f32_16x16x32_bf16 v[46:49], v[152:155], v[184:187], 0
	v_mfma_f32_16x16x32_bf16 v[38:41], v[140:143], v[192:195], 0
	v_mfma_f32_16x16x32_bf16 v[30:33], v[152:155], v[192:195], 0
	v_mfma_f32_16x16x32_bf16 v[22:25], v[140:143], v[200:203], 0
	v_mfma_f32_16x16x32_bf16 v[14:17], v[152:155], v[200:203], 0
	v_mfma_f32_16x16x32_bf16 v[62:65], v[148:151], v[180:183], v[62:65]
	v_mfma_f32_16x16x32_bf16 v[58:61], v[156:159], v[180:183], v[58:61]
	v_mfma_f32_16x16x32_bf16 v[54:57], v[148:151], v[188:191], v[54:57]
	v_mfma_f32_16x16x32_bf16 v[46:49], v[156:159], v[188:191], v[46:49]
	v_mfma_f32_16x16x32_bf16 v[38:41], v[148:151], v[196:199], v[38:41]
	v_mfma_f32_16x16x32_bf16 v[30:33], v[156:159], v[196:199], v[30:33]
	v_mfma_f32_16x16x32_bf16 v[22:25], v[148:151], v[204:207], v[22:25]
	v_mfma_f32_16x16x32_bf16 v[14:17], v[156:159], v[204:207], v[14:17]
	s_setprio 0
	s_setprio 1
	v_mfma_f32_16x16x32_bf16 v[50:53], v[160:163], v[176:179], 0
	v_mfma_f32_16x16x32_bf16 v[42:45], v[168:171], v[176:179], 0
	v_mfma_f32_16x16x32_bf16 v[34:37], v[160:163], v[184:187], 0
	v_mfma_f32_16x16x32_bf16 v[26:29], v[168:171], v[184:187], 0
	v_mfma_f32_16x16x32_bf16 v[18:21], v[160:163], v[192:195], 0
	v_mfma_f32_16x16x32_bf16 v[10:13], v[168:171], v[192:195], 0
	v_mfma_f32_16x16x32_bf16 v[6:9], v[160:163], v[200:203], 0
	v_mfma_f32_16x16x32_bf16 v[2:5], v[168:171], v[200:203], 0
	v_mfma_f32_16x16x32_bf16 v[50:53], v[164:167], v[180:183], v[50:53]
	v_mfma_f32_16x16x32_bf16 v[42:45], v[172:175], v[180:183], v[42:45]
	v_mfma_f32_16x16x32_bf16 v[34:37], v[164:167], v[188:191], v[34:37]
	v_mfma_f32_16x16x32_bf16 v[26:29], v[172:175], v[188:191], v[26:29]
	v_mfma_f32_16x16x32_bf16 v[18:21], v[164:167], v[196:199], v[18:21]
	v_mfma_f32_16x16x32_bf16 v[10:13], v[172:175], v[196:199], v[10:13]
	v_mfma_f32_16x16x32_bf16 v[6:9], v[164:167], v[204:207], v[6:9]
	s_barrier
	v_mfma_f32_16x16x32_bf16 v[2:5], v[172:175], v[204:207], v[2:5]
	s_setprio 0
	s_add_i32 s6, 0, 0x18000
	s_add_i32 s7, 0, 0x1c000
	v_add_u32_e32 v156, s6, v146
	v_add_u32_e32 v172, s7, v146
	ds_read_b128 v[140:143], v156
	ds_read_b128 v[148:151], v156 offset:1024
	ds_read_b128 v[152:155], v156 offset:2048
	ds_read_b128 v[156:159], v156 offset:3072
	ds_read_b128 v[160:163], v172
	ds_read_b128 v[164:167], v172 offset:1024
	ds_read_b128 v[168:171], v172 offset:2048
	ds_read_b128 v[172:175], v172 offset:3072
	s_add_u32 s4, s36, 0x40000
	s_addc_u32 s5, s37, 0
	s_mov_b32 m0, s45
	v_lshl_add_u64 v[228:229], s[4:5], 0, v[134:135]
	ds_read_b128 v[176:179], v147 offset:32768
	ds_read_b128 v[180:183], v147 offset:33792
	ds_read_b128 v[184:187], v147 offset:34816
	ds_read_b128 v[188:191], v147 offset:35840
	ds_read_b128 v[192:195], v147 offset:36864
	ds_read_b128 v[196:199], v147 offset:37888
	ds_read_b128 v[200:203], v147 offset:38912
	ds_read_b128 v[204:207], v147 offset:39936
	global_load_lds_dwordx4 v[228:229], off
	v_lshl_add_u64 v[228:229], s[4:5], 0, v[130:131]
	s_mov_b32 m0, s46
	s_nop 0
	global_load_lds_dwordx4 v[228:229], off
	s_waitcnt vmcnt(8)
	s_waitcnt lgkmcnt(0)
	s_barrier
	s_setprio 1
	s_waitcnt lgkmcnt(0)
	v_mfma_f32_16x16x32_bf16 v[126:129], v[140:143], v[176:179], v[126:129]
	v_mfma_f32_16x16x32_bf16 v[122:125], v[152:155], v[176:179], v[122:125]
	v_mfma_f32_16x16x32_bf16 v[118:121], v[140:143], v[184:187], v[118:121]
	v_mfma_f32_16x16x32_bf16 v[110:113], v[152:155], v[184:187], v[110:113]
	v_mfma_f32_16x16x32_bf16 v[102:105], v[140:143], v[192:195], v[102:105]
	v_mfma_f32_16x16x32_bf16 v[94:97], v[152:155], v[192:195], v[94:97]
	v_mfma_f32_16x16x32_bf16 v[86:89], v[140:143], v[200:203], v[86:89]
	v_mfma_f32_16x16x32_bf16 v[78:81], v[152:155], v[200:203], v[78:81]
	v_mfma_f32_16x16x32_bf16 v[126:129], v[148:151], v[180:183], v[126:129]
	v_mfma_f32_16x16x32_bf16 v[122:125], v[156:159], v[180:183], v[122:125]
	v_mfma_f32_16x16x32_bf16 v[118:121], v[148:151], v[188:191], v[118:121]
	v_mfma_f32_16x16x32_bf16 v[110:113], v[156:159], v[188:191], v[110:113]
	v_mfma_f32_16x16x32_bf16 v[102:105], v[148:151], v[196:199], v[102:105]
	v_mfma_f32_16x16x32_bf16 v[94:97], v[156:159], v[196:199], v[94:97]
	v_mfma_f32_16x16x32_bf16 v[86:89], v[148:151], v[204:207], v[86:89]
	v_mfma_f32_16x16x32_bf16 v[78:81], v[156:159], v[204:207], v[78:81]
	s_setprio 0
	s_setprio 1
	v_mfma_f32_16x16x32_bf16 v[114:117], v[160:163], v[176:179], v[114:117]
	v_mfma_f32_16x16x32_bf16 v[106:109], v[168:171], v[176:179], v[106:109]
	v_mfma_f32_16x16x32_bf16 v[98:101], v[160:163], v[184:187], v[98:101]
	v_mfma_f32_16x16x32_bf16 v[90:93], v[168:171], v[184:187], v[90:93]
	v_mfma_f32_16x16x32_bf16 v[82:85], v[160:163], v[192:195], v[82:85]
	v_mfma_f32_16x16x32_bf16 v[74:77], v[168:171], v[192:195], v[74:77]
	v_mfma_f32_16x16x32_bf16 v[70:73], v[160:163], v[200:203], v[70:73]
	v_mfma_f32_16x16x32_bf16 v[66:69], v[168:171], v[200:203], v[66:69]
	v_mfma_f32_16x16x32_bf16 v[114:117], v[164:167], v[180:183], v[114:117]
	v_mfma_f32_16x16x32_bf16 v[106:109], v[172:175], v[180:183], v[106:109]
	v_mfma_f32_16x16x32_bf16 v[98:101], v[164:167], v[188:191], v[98:101]
	v_mfma_f32_16x16x32_bf16 v[90:93], v[172:175], v[188:191], v[90:93]
	v_mfma_f32_16x16x32_bf16 v[82:85], v[164:167], v[196:199], v[82:85]
	v_mfma_f32_16x16x32_bf16 v[74:77], v[172:175], v[196:199], v[74:77]
	v_mfma_f32_16x16x32_bf16 v[70:73], v[164:167], v[204:207], v[70:73]
	s_barrier
	v_mfma_f32_16x16x32_bf16 v[66:69], v[172:175], v[204:207], v[66:69]
	s_setprio 0
	s_add_i32 s4, s6, s38
	v_lshl_add_u64 v[208:209], v[208:209], 0, s[82:83]
	s_mov_b32 m0, s4
	ds_read_b128 v[176:179], v147 offset:49152
	ds_read_b128 v[180:183], v147 offset:50176
	ds_read_b128 v[184:187], v147 offset:51200
	ds_read_b128 v[188:191], v147 offset:52224
	ds_read_b128 v[192:195], v147 offset:53248
	ds_read_b128 v[196:199], v147 offset:54272
	ds_read_b128 v[200:203], v147 offset:55296
	ds_read_b128 v[204:207], v147 offset:56320
	global_load_lds_dwordx4 v[208:209], off
	s_add_i32 m0, s4, 0x2000
	s_add_u32 s4, s34, 0x40080
	v_lshl_add_u64 v[208:209], v[222:223], 0, s[82:83]
	s_addc_u32 s5, s35, 0
	s_add_i32 s6, s7, s38
	global_load_lds_dwordx4 v[208:209], off
	v_lshl_add_u64 v[208:209], s[4:5], 0, v[0:1]
	s_mov_b32 m0, s6
	s_nop 0
	global_load_lds_dwordx4 v[208:209], off
	v_lshl_add_u64 v[208:209], s[4:5], 0, v[132:133]
	s_add_i32 m0, s6, 0x2000
	s_nop 0
	global_load_lds_dwordx4 v[208:209], off
	v_lshl_add_u64 v[208:209], v[224:225], 0, s[82:83]
	s_mov_b32 m0, s49
	s_nop 0
	global_load_lds_dwordx4 v[208:209], off
	v_lshl_add_u64 v[208:209], v[226:227], 0, s[82:83]
	s_mov_b32 m0, s50
	s_nop 0
	global_load_lds_dwordx4 v[208:209], off
	s_waitcnt vmcnt(8)
	s_waitcnt lgkmcnt(0)
	s_barrier
	s_setprio 1
	s_waitcnt lgkmcnt(0)
	v_mfma_f32_16x16x32_bf16 v[62:65], v[140:143], v[176:179], v[62:65]
	v_mfma_f32_16x16x32_bf16 v[58:61], v[152:155], v[176:179], v[58:61]
	v_mfma_f32_16x16x32_bf16 v[54:57], v[140:143], v[184:187], v[54:57]
	v_mfma_f32_16x16x32_bf16 v[46:49], v[152:155], v[184:187], v[46:49]
	v_mfma_f32_16x16x32_bf16 v[38:41], v[140:143], v[192:195], v[38:41]
	v_mfma_f32_16x16x32_bf16 v[30:33], v[152:155], v[192:195], v[30:33]
	v_mfma_f32_16x16x32_bf16 v[22:25], v[140:143], v[200:203], v[22:25]
	v_mfma_f32_16x16x32_bf16 v[14:17], v[152:155], v[200:203], v[14:17]
	v_mfma_f32_16x16x32_bf16 v[62:65], v[148:151], v[180:183], v[62:65]
	v_mfma_f32_16x16x32_bf16 v[58:61], v[156:159], v[180:183], v[58:61]
	v_mfma_f32_16x16x32_bf16 v[54:57], v[148:151], v[188:191], v[54:57]
	v_mfma_f32_16x16x32_bf16 v[46:49], v[156:159], v[188:191], v[46:49]
	v_mfma_f32_16x16x32_bf16 v[38:41], v[148:151], v[196:199], v[38:41]
	v_mfma_f32_16x16x32_bf16 v[30:33], v[156:159], v[196:199], v[30:33]
	v_mfma_f32_16x16x32_bf16 v[22:25], v[148:151], v[204:207], v[22:25]
	v_mfma_f32_16x16x32_bf16 v[14:17], v[156:159], v[204:207], v[14:17]
	s_setprio 0
	s_setprio 1
	v_mfma_f32_16x16x32_bf16 v[50:53], v[160:163], v[176:179], v[50:53]
	v_mfma_f32_16x16x32_bf16 v[42:45], v[168:171], v[176:179], v[42:45]
	v_mfma_f32_16x16x32_bf16 v[34:37], v[160:163], v[184:187], v[34:37]
	v_mfma_f32_16x16x32_bf16 v[26:29], v[168:171], v[184:187], v[26:29]
	v_mfma_f32_16x16x32_bf16 v[18:21], v[160:163], v[192:195], v[18:21]
	v_mfma_f32_16x16x32_bf16 v[10:13], v[168:171], v[192:195], v[10:13]
	v_mfma_f32_16x16x32_bf16 v[6:9], v[160:163], v[200:203], v[6:9]
	v_mfma_f32_16x16x32_bf16 v[2:5], v[168:171], v[200:203], v[2:5]
	v_mfma_f32_16x16x32_bf16 v[50:53], v[164:167], v[180:183], v[50:53]
	v_mfma_f32_16x16x32_bf16 v[42:45], v[172:175], v[180:183], v[42:45]
	v_mfma_f32_16x16x32_bf16 v[34:37], v[164:167], v[188:191], v[34:37]
	v_mfma_f32_16x16x32_bf16 v[26:29], v[172:175], v[188:191], v[26:29]
	v_mfma_f32_16x16x32_bf16 v[18:21], v[164:167], v[196:199], v[18:21]
	v_mfma_f32_16x16x32_bf16 v[10:13], v[172:175], v[196:199], v[10:13]
	v_mfma_f32_16x16x32_bf16 v[6:9], v[164:167], v[204:207], v[6:9]
	s_barrier
	v_mfma_f32_16x16x32_bf16 v[2:5], v[172:175], v[204:207], v[2:5]
	s_setprio 0
	s_add_i32 s59, s59, 2
	s_add_u32 s30, s30, 0x100
	s_addc_u32 s31, s31, 0
	s_add_u32 s68, s68, 0x100
	s_addc_u32 s69, s69, 0
	s_cmp_gt_u32 s59, 13
	.p2align 6
